# MLA loop: wave-uniform branch helper masks formed by one SALU op instead of v_cndmask+v_cmp (2 sites), on top of the scalar row-sum adds
# speedup vs baseline: 1.0038x; 1.0021x over previous
; #define LAS __attribute__((address_space(3)))
; __device__ __forceinline__ void finishSM(f32x16& p0, f32x16& p1, float alpha, float& l_reg, bf16x8& pa0, bf16x8& pa1, bf16x8& pa2, bf16x8& pa3) {
; #pragma unroll
;     for (int r = 0; r < 16; ++r) p1[r] = __builtin_amdgcn_exp2f(p1[r]);
;     typedef float f32x2 __attribute__((ext_vector_type(2)));
;     f32x2 s2 = (f32x2){p0[0], p0[1]};
; #pragma unroll
;     for (int r = 2; r < 16; r += 2) s2 += (f32x2){p0[r], p0[r + 1]};
; #pragma unroll
;     for (int r = 0; r < 16; r += 2) s2 += (f32x2){p1[r], p1[r + 1]};
;     float ps = s2.x + s2.y;
;     { auto rr = __builtin_amdgcn_permlane32_swap(__float_as_uint(ps), __float_as_uint(ps), false, false);
;       ps = __uint_as_float(rr[0]) + __uint_as_float(rr[1]); }
;     l_reg = l_reg * alpha + ps;
;     ...
;     PK4(p0, 0, pa0); PK4(p0, 8, pa1); PK4(p1, 0, pa2); PK4(p1, 8, pa3);
;     ...
; }
; template <int MODE> __device__ __forceinline__ void qkt(f32x16& p0, f32x16& p1, const LAS unsigned char* Kt, const LAS unsigned char* Krt, const bf16x8* qr, int r32, int hi, int comp) {
;     p0 = f32x16{}; p1 = f32x16{};
;     constexpr int NDN = MODE ? 8 : 4;
; #pragma unroll
;     for (int d0 = 0; d0 < NDN; ++d0) { const int cb = ((MODE ? 0 : comp * 64) + d0 * 16 + hi * 8) * 2;
;         const bf16x8 b0 = *(const LAS bf16x8*)(Kt + KSWZ(r32, cb));
;         const bf16x8 b1 = *(const LAS bf16x8*)(Kt + KSWZ(32 + r32, cb));
;         p0 = __builtin_amdgcn_mfma_f32_32x32x16_bf16(b0, qr[d0], p0, 0, 0, 0);
;         p1 = __builtin_amdgcn_mfma_f32_32x32x16_bf16(b1, qr[d0], p1, 0, 0, 0); }
;     if constexpr (MODE == 1) {
; #pragma unroll
;         for (int d0 = 0; d0 < 4; ++d0) { const int cb = (d0 * 16 + hi * 8) * 2;
;             const bf16x8 b0 = *(const LAS bf16x8*)(Krt + KRSWZ(r32, cb));
;             const bf16x8 b1 = *(const LAS bf16x8*)(Krt + KRSWZ(32 + r32, cb));
;             p0 = __builtin_amdgcn_mfma_f32_32x32x16_bf16(b0, qr[8 + d0], p0, 0, 0, 0);
;             p1 = __builtin_amdgcn_mfma_f32_32x32x16_bf16(b1, qr[8 + d0], p1, 0, 0, 0); }
;     }
; }
.LBB0_600:
	s_mov_b32 s93, s92
	s_mov_b32 s92, s2
	s_andn2_b64 s[2:3], exec, s[66:67]
	s_andn2_b64 vcc, exec, s[66:67]
	v_lshl_add_u64 v[194:195], v[186:187], 0, s[38:39]
	s_cbranch_vccnz .LBB0_602
	v_lshl_add_u64 v[96:97], v[190:191], 0, s[38:39]
	s_mov_b32 m0, s69
	v_lshl_add_u64 v[96:97], v[96:97], 0, s[40:41]
	global_load_lds_dwordx4 v[96:97], off
	v_lshl_add_u64 v[96:97], v[192:193], 0, s[38:39]
	v_lshl_add_u64 v[96:97], v[96:97], 0, s[40:41]
	s_mov_b32 m0, s20
	s_mov_b64 s[4:5], 0xf504000
	global_load_lds_dwordx4 v[96:97], off
	v_lshl_add_u64 v[96:97], v[188:189], 0, s[38:39]
	v_lshl_add_u64 v[96:97], v[96:97], 0, s[4:5]
	s_add_i32 m0, s85, 0x14000
	s_mov_b64 s[4:5], 0x15840100
	s_add_i32 s16, s84, s83
	global_load_lds_dwordx4 v[96:97], off
	v_lshl_add_u64 v[96:97], v[194:195], 0, s[4:5]
	s_mov_b32 m0, s16
	s_mov_b64 s[4:5], 0x15840180
	global_load_lds_dwordx4 v[96:97], off
	v_lshl_add_u64 v[96:97], v[194:195], 0, s[4:5]
	s_add_i32 m0, s16, 0x400
	s_nop 0
	global_load_lds_dwordx4 v[96:97], off
.LBB0_602:
	v_add_u32_e32 v231, v229, v204
	ds_read_b128 v[96:99], v231
	ds_read_b128 v[100:103], v231 offset:8192
	v_add_u32_e32 v232, v229, v206
	ds_read_b128 v[234:237], v232
	ds_read_b128 v[238:241], v232 offset:8192
	v_add_u32_e32 v233, v229, v208
	s_waitcnt lgkmcnt(0)
	v_mfma_f32_32x32x16_bf16 v[112:127], v[96:99], v[172:175], 0
	v_exp_f32_e32 v198, v84
	v_exp_f32_e32 v199, v85
	v_add_f32_e32 v84, v64, v66
	v_add_f32_e32 v85, v65, v67
	v_exp_f32_e32 v80, v80
	v_add_f32_e32 v84, v68, v84
	v_add_f32_e32 v85, v69, v85
	v_exp_f32_e32 v81, v81
	v_add_f32_e32 v84, v70, v84
	v_add_f32_e32 v85, v71, v85
	v_mfma_f32_32x32x16_bf16 v[96:111], v[100:103], v[172:175], 0
	v_add_f32_e64 v84, v72, v84
	v_add_f32_e64 v85, v73, v85
	v_add_u32_e32 v242, v230, v226
	v_exp_f32_e32 v82, v82
	v_exp_f32_e32 v83, v83
	v_add_f32_e32 v84, v74, v84
	v_add_f32_e32 v85, v75, v85
	v_exp_f32_e32 v200, v86
	v_add_f32_e32 v84, v76, v84
	v_add_f32_e32 v85, v77, v85
	v_mfma_f32_32x32x16_bf16 v[112:127], v[234:237], v[168:171], v[112:127]
	v_exp_f32_e32 v201, v87
	v_add_f32_e32 v84, v78, v84
	v_add_f32_e32 v85, v79, v85
	v_exp_f32_e32 v88, v88
	v_exp_f32_e32 v89, v89
	v_add_f32_e32 v84, v80, v84
	v_add_f32_e32 v85, v81, v85
	v_exp_f32_e32 v90, v90
	v_exp_f32_e32 v91, v91
	v_mfma_f32_32x32x16_bf16 v[96:111], v[238:241], v[168:171], v[96:111]
	ds_read_b128 v[234:237], v233
	ds_read_b128 v[238:241], v233 offset:8192
	v_add_f32_e64 v84, v82, v84
	v_add_f32_e64 v85, v83, v85
	v_exp_f32_e32 v92, v92
	v_exp_f32_e32 v93, v93
	v_add_f32_e32 v84, v198, v84
	v_add_f32_e32 v85, v199, v85
	v_exp_f32_e32 v94, v94
	v_exp_f32_e32 v95, v95
	s_waitcnt lgkmcnt(0)
	v_mfma_f32_32x32x16_bf16 v[112:127], v[234:237], v[164:167], v[112:127]
	v_add_u32_e32 v234, v229, v210
	v_add_u32_e32 v235, v229, v212
	v_add_f32_e64 v84, v200, v84
	v_add_f32_e64 v85, v201, v85
	v_add_f32_e64 v84, v88, v84
	v_add_f32_e64 v85, v89, v85
	v_add_f32_e32 v84, v90, v84
	v_add_f32_e32 v85, v91, v85
	v_mfma_f32_32x32x16_bf16 v[96:111], v[238:241], v[164:167], v[96:111]
	ds_read_b128 v[236:239], v234
	ds_read_b128 v[244:247], v234 offset:8192
	v_add_f32_e64 v84, v92, v84
	v_add_f32_e64 v85, v93, v85
	v_add_f32_e64 v84, v94, v84
	v_add_f32_e64 v85, v95, v85
	v_pk_add_f32 v[196:197], v[84:85], v[84:85] op_sel:[0,1] op_sel_hi:[1,0]
	s_waitcnt lgkmcnt(0)
	v_mfma_f32_32x32x16_bf16 v[112:127], v[236:239], v[160:163], v[112:127]
	v_mfma_f32_32x32x16_bf16 v[96:111], v[244:247], v[160:163], v[96:111]
	ds_read_b128 v[236:239], v235
	ds_read_b128 v[244:247], v235 offset:8192
	s_waitcnt lgkmcnt(0)
	v_mfma_f32_32x32x16_bf16 v[112:127], v[236:239], v[156:159], v[112:127]
	v_add_u32_e32 v236, v229, v214
	v_add_u32_e32 v237, v229, v216
	v_mfma_f32_32x32x16_bf16 v[96:111], v[244:247], v[156:159], v[96:111]
	ds_read_b128 v[238:241], v236
	ds_read_b128 v[244:247], v236 offset:8192
	s_waitcnt lgkmcnt(0)
	v_mfma_f32_32x32x16_bf16 v[112:127], v[238:241], v[152:155], v[112:127]
	v_mfma_f32_32x32x16_bf16 v[96:111], v[244:247], v[152:155], v[96:111]
	ds_read_b128 v[238:241], v237
	ds_read_b128 v[244:247], v237 offset:8192
	s_waitcnt lgkmcnt(0)
	v_mfma_f32_32x32x16_bf16 v[112:127], v[238:241], v[148:151], v[112:127]
	v_add_u32_e32 v238, v229, v218
	v_add_u32_e32 v239, v230, v220
	v_add_u32_e32 v241, v230, v222
	v_add_u32_e32 v240, v230, v224
	v_mfma_f32_32x32x16_bf16 v[96:111], v[244:247], v[148:151], v[96:111]
	ds_read_b128 v[244:247], v238
	ds_read_b128 v[248:251], v238 offset:8192
	s_waitcnt lgkmcnt(0)
	v_mfma_f32_32x32x16_bf16 v[112:127], v[244:247], v[144:147], v[112:127]
	v_mfma_f32_32x32x16_bf16 v[96:111], v[248:251], v[144:147], v[96:111]
	ds_read_b128 v[244:247], v239
	ds_read_b128 v[248:251], v239 offset:4096
	s_waitcnt lgkmcnt(0)
	v_mfma_f32_32x32x16_bf16 v[112:127], v[244:247], v[140:143], v[112:127]
	v_mfma_f32_32x32x16_bf16 v[96:111], v[248:251], v[140:143], v[96:111]
	ds_read_b128 v[244:247], v241
	ds_read_b128 v[248:251], v241 offset:4096
	s_waitcnt lgkmcnt(0)
	v_mfma_f32_32x32x16_bf16 v[112:127], v[244:247], v[136:139], v[112:127]
	v_mfma_f32_32x32x16_bf16 v[96:111], v[248:251], v[136:139], v[96:111]
	ds_read_b128 v[244:247], v240
	ds_read_b128 v[248:251], v240 offset:4096
	s_waitcnt lgkmcnt(0)
	v_mfma_f32_32x32x16_bf16 v[112:127], v[244:247], v[132:135], v[112:127]
	v_mfma_f32_32x32x16_bf16 v[96:111], v[248:251], v[132:135], v[96:111]
	ds_read_b128 v[244:247], v242
	ds_read_b128 v[248:251], v242 offset:4096
	v_cvt_pk_bf16_f32 v84, v64, v65
	v_cvt_pk_bf16_f32 v85, v66, v67
	v_cvt_pk_bf16_f32 v86, v68, v69
	v_cvt_pk_bf16_f32 v87, v70, v71
	v_cvt_pk_bf16_f32 v72, v72, v73
	v_cvt_pk_bf16_f32 v73, v74, v75
	s_waitcnt lgkmcnt(0)
	v_mfma_f32_32x32x16_bf16 v[112:127], v[244:247], v[128:131], v[112:127]
	v_mov_b32_e32 v245, v196
	v_cvt_pk_bf16_f32 v74, v76, v77
	v_cvt_pk_bf16_f32 v75, v78, v79
	v_cvt_pk_bf16_f32 v76, v80, v81
	v_cvt_pk_bf16_f32 v77, v82, v83
	v_cvt_pk_bf16_f32 v78, v198, v199
	v_cvt_pk_bf16_f32 v79, v200, v201
	v_mfma_f32_32x32x16_bf16 v[96:111], v[248:251], v[128:131], v[96:111]
	v_cvt_pk_bf16_f32 v80, v88, v89
	v_cvt_pk_bf16_f32 v81, v90, v91
	v_cvt_pk_bf16_f32 v82, v92, v93
	v_cvt_pk_bf16_f32 v83, v94, v95
	s_nop 0
	v_permlane32_swap_b32_e32 v196, v245
	s_andn2_b64 s[4:5], exec, s[70:71]
	s_andn2_b64 vcc, exec, s[70:71]
	s_cbranch_vccnz .LBB0_604
	s_waitcnt vmcnt(0) lgkmcnt(0)
	s_barrier
